# D unit: first tile of each sequence uses MFMA C=0 and skips the rescale (no 32-register zero fill per sequence)
# speedup vs baseline: 1.0054x; 1.0054x over previous
; #define LAS __attribute__((address_space(3)))
; DI s16x4 vtr(LAS const unsigned char* p) { return __builtin_bit_cast(s16x4, __builtin_amdgcn_ds_read_tr16_b64_v4i16((LAS v4i16_t*)p)); }
; #define MFMA32(a, b, c) __builtin_amdgcn_mfma_f32_32x32x16_bf16((a), (b), (c), 0, 0, 0)
; template <bool MASKED>
; DI void attn_tile_sw(int MODE, LAS const unsigned char* kst, LAS const unsigned char* vst, const bf16x8 (&qf)[4], float bstep, float ca, int lane, f32x16& o0, f32x16& o1, float& m, float& l) {
;     ...
;     f32x16 s; { const float sb = bstep * (float)(4 * hh - qq);
; #pragma unroll
;         for (int i = 0; i < 16; ++i) s[i] = bstep * (float)((i & 3) + 8 * (i >> 2)) + sb; }
;     {   bf16x8 kf[4];
; #pragma unroll
;         for (int st = 0; st < 4; ++st) kf[st] = *(LAS const bf16x8*)(kst + qq * 128 + (((2 * st + hh) ^ (qq & 7)) << 4));
; #pragma unroll
;         for (int st = 0; st < 4; ++st) s = MFMA32(kf[st], qf[st], s); }
;     const int q4 = (lane & 15) >> 2, p = lane & 3, blk = (lane >> 4) & 1, x = 4 * hh + q4;
;     LAS const unsigned char* vb = vst + x * 128 + 8 * (p & 1);
;     const int ch0 = ((2 * blk + (p >> 1)) ^ x) << 4, ch1 = ((4 + 2 * blk + (p >> 1)) ^ x) << 4;
;     const s16x4 va0 = vtr(vb + ch0), va1 = vtr(vb + 8 * 128 + ch0), vb0 = vtr(vb + ch1), vb1 = vtr(vb + 8 * 128 + ch1);
;     const s16x4 vc0 = vtr(vb + 16 * 128 + ch0), vc1 = vtr(vb + 24 * 128 + ch0), vd0 = vtr(vb + 16 * 128 + ch1), vd1 = vtr(vb + 24 * 128 + ch1);
;     if (MASKED) { const int dq = (MODE == 1) ? (qq - 4 * hh) : (4 * hh - qq);
; #pragma unroll
;         for (int r = 0; r < 16; ++r) { const int kq = (r & 3) + 8 * (r >> 2); s[r] = (((MODE == 1) ? kq : -kq) < dq) ? NEG : s[r]; } }
; DI void unit_dilated2(int u, const bf16* __restrict__ Q, const bf16* __restrict__ K, const bf16* __restrict__ V, const bf16* __restrict__ G, bf16* __restrict__ MIX, LAS unsigned char* lds, int tid, int lane, int wave) {
;     ...
;         const DilWT nw = dil_wt(seq < 5 ? seq + 1 : 5, wave, b, h, T0, qq, slope2);
;         bf16x8 qn[4];
; #pragma unroll
;         for (int st = 0; st < 4; ++st) qn[st] = *(const bf16x8*)(Q + nw.qrow * 512 + h * 64 + 16 * st + 8 * hh);
;         f32x16 o0, o1;
; #pragma unroll
;         for (int i = 0; i < 16; ++i) { o0[i] = 0.f; o1[i] = 0.f; }
;         float m = NEG, l = 0.f;
.LBB0_755:
	s_mov_b32 s35, s44
	s_add_i32 s44, s44, 1
	s_cmp_lg_u32 s35, 5
	s_cselect_b64 s[22:23], -1, 0
	s_and_b64 s[0:1], s[22:23], exec
	s_cselect_b32 s0, s44, 5
	s_lshl_b32 s1, s0, 3
	s_and_b32 s1, s1, 8
	s_and_b32 s0, s0, 14
	s_add_i32 s1, s1, s33
	s_sub_i32 s8, 4, s0
	s_mov_b64 s[2:3], s[16:17]
	s_lshr_b32 s16, s1, s8
	s_lshr_b32 s8, 16, s0
	s_add_i32 s8, s8, -1
	s_and_b32 s1, s1, s8
	s_lshl_b32 s9, s1, 5
	v_or_b32_e32 v3, s9, v228
	v_lshlrev_b32_e32 v3, s0, v3
	v_mov_b32_e32 v241, v184
	v_add_u32_e32 v184, s16, v3
	v_ashrrev_i32_e32 v185, 31, v184
	v_lshl_add_u64 v[4:5], s[10:11], 0, v[184:185]
	v_lshlrev_b64 v[4:5], 10, v[4:5]
	s_waitcnt vmcnt(0)
	v_mov_b64_e32 v[164:165], v[132:133]
	v_mov_b64_e32 v[168:169], v[124:125]
	v_mov_b64_e32 v[172:173], v[120:121]
	v_mov_b64_e32 v[176:177], v[116:117]
	v_lshl_add_u64 v[4:5], v[196:197], 0, v[4:5]
	v_mov_b64_e32 v[162:163], v[130:131]
	v_mov_b64_e32 v[166:167], v[122:123]
	v_mov_b64_e32 v[170:171], v[118:119]
	v_mov_b64_e32 v[174:175], v[114:115]
	global_load_dwordx4 v[114:117], v[4:5], off
	global_load_dwordx4 v[118:121], v[4:5], off offset:32
	global_load_dwordx4 v[122:125], v[4:5], off offset:64
	global_load_dwordx4 v[130:133], v[4:5], off offset:96
	s_lshr_b32 s8, s34, s0
	s_add_i32 s1, s9, s8
	s_add_i32 s8, s1, 0xffffff80
	s_ashr_i32 s9, s8, 31
	s_lshl_b32 s38, 0x200, s0
	s_lshl_b64 s[8:9], s[8:9], s0
	s_add_u32 s16, s12, s16
	s_addc_u32 s17, s13, 0
	s_add_u32 s8, s16, s8
	s_addc_u32 s9, s17, s9
	s_lshl_b64 s[8:9], s[8:9], 9
	s_or_b64 s[16:17], s[8:9], s[14:15]
	s_mov_b64 s[20:21], s[18:19]
	s_mov_b64 s[18:19], s[38:39]
	v_mov_b32_e32 v5, s17
	v_or_b32_e32 v4, s16, v188
	s_lshl_b32 s38, s38, 7
	s_add_i32 s8, s0, 9
	v_lshl_add_u64 v[4:5], v[4:5], 0, s[38:39]
	v_lshlrev_b64 v[6:7], s8, v[186:187]
	v_lshl_add_u64 v[6:7], v[4:5], 0, v[6:7]
	v_lshlrev_b64 v[6:7], 1, v[6:7]
	v_lshl_add_u64 v[200:201], s[76:77], 0, v[6:7]
	v_lshl_add_u64 v[202:203], s[80:81], 0, v[6:7]
	v_lshlrev_b64 v[6:7], s8, v[190:191]
	v_lshl_add_u64 v[6:7], v[4:5], 0, v[6:7]
	v_lshlrev_b64 v[6:7], 1, v[6:7]
	v_lshl_add_u64 v[204:205], s[76:77], 0, v[6:7]
	v_lshl_add_u64 v[206:207], s[80:81], 0, v[6:7]
	v_lshlrev_b64 v[6:7], s8, v[192:193]
	v_lshl_add_u64 v[6:7], v[4:5], 0, v[6:7]
	v_lshlrev_b64 v[6:7], 1, v[6:7]
	v_lshl_add_u64 v[208:209], s[76:77], 0, v[6:7]
	v_lshl_add_u64 v[210:211], s[80:81], 0, v[6:7]
	v_lshlrev_b64 v[6:7], s8, v[194:195]
	v_lshl_add_u64 v[4:5], v[4:5], 0, v[6:7]
	v_lshlrev_b64 v[4:5], 1, v[4:5]
	v_lshl_add_u64 v[212:213], s[76:77], 0, v[4:5]
	v_lshl_add_u64 v[214:215], s[80:81], 0, v[4:5]
	v_mul_lo_u32 v216, s20, v186
	s_mul_i32 s8, s20, 0x60
	s_add_u32 s8, s2, s8
	s_addc_u32 s9, s3, 0
	s_lshl_b64 s[8:9], s[8:9], 1
	s_add_u32 s8, s8, s76
	s_addc_u32 s9, s9, s77
	s_sub_u32 s3, s80, s76
	s_lshl_b32 s2, s20, 4
	v_add_lshl_u32 v216, v216, v188, 1
	v_add_u32_e32 v217, s2, v216
	v_add_u32_e32 v218, s2, v217
	v_add_u32_e32 v219, s2, v218
	v_add_u32_e32 v220, s3, v216
	v_add_u32_e32 v221, s3, v217
	v_add_u32_e32 v222, s3, v218
	v_add_u32_e32 v223, s3, v219
	v_mul_f32_e32 v4, v199, v231
	v_mul_f32_e32 v198, 0, v199
	v_mov_b32_e32 v6, v199
	v_mov_b32_e32 v16, v2
	v_mov_b32_e32 v17, v2
	v_pk_add_f32 v[18:19], v[198:199], v[4:5] op_sel_hi:[1,0]
	v_pk_fma_f32 v[20:21], v[6:7], s[96:97], v[4:5] op_sel_hi:[0,1,0]
	v_pk_fma_f32 v[22:23], v[6:7], s[74:75], v[4:5] op_sel_hi:[0,1,0]
	v_pk_fma_f32 v[24:25], v[6:7], s[82:83], v[4:5] op_sel_hi:[0,1,0]
	v_pk_fma_f32 v[26:27], v[6:7], s[86:87], v[4:5] op_sel_hi:[0,1,0]
	v_pk_fma_f32 v[28:29], v[6:7], s[90:91], v[4:5] op_sel_hi:[0,1,0]
	v_pk_fma_f32 v[30:31], v[6:7], s[68:69], v[4:5] op_sel_hi:[0,1,0]
	v_pk_fma_f32 v[32:33], v[6:7], s[70:71], v[4:5] op_sel_hi:[0,1,0]
	v_cmp_le_i32_e32 vcc, 0, v232
	v_cmp_ge_i32_e64 s[26:27], 0, v232
	v_cmp_le_i32_e64 s[2:3], 1, v232
	v_cndmask_b32_e32 v34, v226, v18, vcc
	v_cmp_ge_i32_e32 vcc, 1, v232
	v_cndmask_b32_e64 v50, v226, v18, s[26:27]
	v_cmp_le_i32_e64 s[26:27], 2, v232
	v_cndmask_b32_e64 v35, v226, v19, s[2:3]
	v_cmp_ge_i32_e64 s[2:3], 2, v232
	v_cndmask_b32_e32 v51, v226, v19, vcc
	v_cmp_le_i32_e32 vcc, 3, v232
	v_cndmask_b32_e64 v36, v226, v20, s[26:27]
	v_cmp_ge_i32_e64 s[26:27], 3, v232
	v_cndmask_b32_e64 v52, v226, v20, s[2:3]
	v_cmp_le_i32_e64 s[2:3], 8, v232
	v_cndmask_b32_e32 v37, v226, v21, vcc
	v_cmp_ge_i32_e32 vcc, 8, v232
	v_cndmask_b32_e64 v53, v226, v21, s[26:27]
	v_cmp_le_i32_e64 s[26:27], 9, v232
	v_cndmask_b32_e64 v38, v226, v22, s[2:3]
	v_cmp_ge_i32_e64 s[2:3], 9, v232
	v_cndmask_b32_e32 v54, v226, v22, vcc
	v_cmp_le_i32_e32 vcc, 10, v232
	v_cndmask_b32_e64 v39, v226, v23, s[26:27]
	v_cmp_ge_i32_e64 s[26:27], 10, v232
	v_cndmask_b32_e64 v55, v226, v23, s[2:3]
	v_cmp_le_i32_e64 s[2:3], 11, v232
	v_cndmask_b32_e32 v40, v226, v24, vcc
	v_cmp_ge_i32_e32 vcc, 11, v232
	v_cndmask_b32_e64 v56, v226, v24, s[26:27]
	v_cmp_le_i32_e64 s[26:27], 16, v232
	v_cndmask_b32_e64 v41, v226, v25, s[2:3]
	v_cmp_ge_i32_e64 s[2:3], 16, v232
	v_cndmask_b32_e32 v57, v226, v25, vcc
	v_cmp_le_i32_e32 vcc, 17, v232
	v_cndmask_b32_e64 v42, v226, v26, s[26:27]
	v_cmp_ge_i32_e64 s[26:27], 17, v232
	v_cndmask_b32_e64 v58, v226, v26, s[2:3]
	v_cmp_le_i32_e64 s[2:3], 18, v232
	v_cndmask_b32_e32 v43, v226, v27, vcc
	v_cmp_ge_i32_e32 vcc, 18, v232
	v_cndmask_b32_e64 v59, v226, v27, s[26:27]
	v_cmp_le_i32_e64 s[26:27], 19, v232
	v_cndmask_b32_e64 v44, v226, v28, s[2:3]
	v_cmp_ge_i32_e64 s[2:3], 19, v232
	v_cndmask_b32_e32 v60, v226, v28, vcc
	v_cmp_le_i32_e32 vcc, 24, v232
	v_cndmask_b32_e64 v45, v226, v29, s[26:27]
	v_cmp_ge_i32_e64 s[26:27], 24, v232
	v_cndmask_b32_e64 v61, v226, v29, s[2:3]
	v_cmp_le_i32_e64 s[2:3], 25, v232
	v_cndmask_b32_e32 v46, v226, v30, vcc
	v_cmp_ge_i32_e32 vcc, 25, v232
	v_cndmask_b32_e64 v62, v226, v30, s[26:27]
	v_cmp_le_i32_e64 s[26:27], 26, v232
	v_cndmask_b32_e64 v47, v226, v31, s[2:3]
	v_cmp_ge_i32_e64 s[2:3], 26, v232
	v_cndmask_b32_e32 v63, v226, v31, vcc
	v_cmp_le_i32_e32 vcc, 27, v232
	v_cndmask_b32_e64 v48, v226, v32, s[26:27]
	v_cmp_ge_i32_e64 s[26:27], 27, v232
	v_cndmask_b32_e64 v64, v226, v32, s[2:3]
	v_cndmask_b32_e32 v49, v226, v33, vcc
	v_cndmask_b32_e64 v65, v226, v33, s[26:27]
	s_lshl_b32 s2, s20, 6
	s_mov_b32 s31, 4
	s_mov_b32 s51, 0
	v_mov_b32_e32 v198, 0xf149f2ca
	v_mov_b32_e32 v185, 0

; #define LAS __attribute__((address_space(3)))
; template <bool MASKED>
; DI void attn_tile_sw(int MODE, LAS const unsigned char* kst, LAS const unsigned char* vst, const bf16x8 (&qf)[4], float bstep, float ca, int lane, f32x16& o0, f32x16& o1, float& m, float& l) {
;     ...
;         for (int st = 0; st < 4; ++st) kf[st] = *(LAS const bf16x8*)(kst + qq * 128 + (((2 * st + hh) ^ (qq & 7)) << 4));
; #pragma unroll
;         for (int st = 0; st < 4; ++st) s = MFMA32(kf[st], qf[st], s); }
;     const int q4 = (lane & 15) >> 2, p = lane & 3, blk = (lane >> 4) & 1, x = 4 * hh + q4;
;     LAS const unsigned char* vb = vst + x * 128 + 8 * (p & 1);
;     const int ch0 = ((2 * blk + (p >> 1)) ^ x) << 4, ch1 = ((4 + 2 * blk + (p >> 1)) ^ x) << 4;
;     const s16x4 va0 = vtr(vb + ch0), va1 = vtr(vb + 8 * 128 + ch0), vb0 = vtr(vb + ch1), vb1 = vtr(vb + 8 * 128 + ch1);
;     const s16x4 vc0 = vtr(vb + 16 * 128 + ch0), vc1 = vtr(vb + 24 * 128 + ch0), vd0 = vtr(vb + 16 * 128 + ch1), vd1 = vtr(vb + 24 * 128 + ch1);
;     if (MASKED) { const int dq = (MODE == 1) ? (qq - 4 * hh) : (4 * hh - qq);
; #pragma unroll
;         for (int r = 0; r < 16; ++r) { const int kq = (r & 3) + 8 * (r >> 2); s[r] = (((MODE == 1) ? kq : -kq) < dq) ? NEG : s[r]; } }
;     float tmax = vmax3(s[0], s[1], s[2]);
;     tmax = vmax3(tmax, s[3], s[4]); tmax = vmax3(tmax, s[5], s[6]); tmax = vmax3(tmax, s[7], s[8]); tmax = vmax3(tmax, s[9], s[10]);
;     tmax = vmax3(tmax, s[11], s[12]); tmax = vmax3(tmax, s[13], s[14]); tmax = fmaxf(tmax, s[15]);
;     tmax = half_max(tmax);
;     const float mn = fmaxf(m, tmax + ca), mrel = mn - ca;
;     if (__builtin_amdgcn_ballot_w64(mn > m) != 0ull) { const float alpha = fexp2(m - mn); l *= alpha;
; #pragma unroll
;         for (int i = 0; i < 16; ++i) { o0[i] *= alpha; o1[i] *= alpha; } }
;     m = mn;
;     float ps = 0.f;
; #pragma unroll
;     for (int r = 0; r < 16; ++r) { s[r] = fexp2(s[r] - mrel); ps += s[r]; }
;     l += half_sum(ps);
;     v4u pa, pb;
;     pa.x = cvtpk(s[0], s[1]); pa.y = cvtpk(s[2], s[3]); pa.z = cvtpk(s[4], s[5]); pa.w = cvtpk(s[6], s[7]);
;     pb.x = cvtpk(s[8], s[9]); pb.y = cvtpk(s[10], s[11]); pb.z = cvtpk(s[12], s[13]); pb.w = cvtpk(s[14], s[15]);
;     const bf16x8 p0 = __builtin_bit_cast(bf16x8, pa), p1 = __builtin_bit_cast(bf16x8, pb);
;     o0 = MFMA32(__builtin_shufflevector(va0, va1, 0, 1, 2, 3, 4, 5, 6, 7), p0, o0);
.Ldil_qk_join:
	ds_read_b128 v[4:7], v237
	ds_read_b128 v[12:15], v238
	s_waitcnt lgkmcnt(2)
	v_mfma_f32_32x32x16_bf16 v[98:113], v[8:11], v[170:173], v[98:113]
	ds_read_b64_tr_b16 v[178:179], v239 offset:4096
	ds_read_b64_tr_b16 v[180:181], v239 offset:5120
	ds_read_b64_tr_b16 v[8:9], v239 offset:6144
	ds_read_b64_tr_b16 v[10:11], v239 offset:7168
	s_waitcnt lgkmcnt(5)
	v_mfma_f32_32x32x16_bf16 v[98:113], v[4:7], v[166:169], v[98:113]
	s_waitcnt lgkmcnt(4)
	v_mfma_f32_32x32x16_bf16 v[98:113], v[12:15], v[162:165], v[98:113]
	ds_read_b64_tr_b16 v[12:13], v240 offset:4096
	ds_read_b64_tr_b16 v[14:15], v240 offset:5120
	ds_read_b64_tr_b16 v[4:5], v240 offset:6144
	ds_read_b64_tr_b16 v[6:7], v240 offset:7168
	v_cvt_f32_i32_e32 v3, s51
	s_cmp_le_i32 s31, s47
	s_cselect_b64 s[26:27], -1, 0
	v_mul_f32_e64 v3, -v199, v3
	s_add_i32 s51, s51, 32
	s_add_i32 s31, s31, -1
	s_nop 1
	v_max3_f32 v17, v98, v99, v100
	v_max3_f32 v16, v101, v102, v103
	v_max3_f32 v17, v17, v104, v105
	v_max3_f32 v16, v16, v106, v107
	v_max3_f32 v17, v17, v108, v109
	v_max3_f32 v16, v16, v110, v111
	v_max3_f32 v17, v17, v112, v113
	v_max_f32_e32 v17, v17, v16
	v_mov_b32_e32 v16, v17
	s_nop 1
	v_permlane32_swap_b32_e32 v17, v16
	v_max_f32_e32 v17, v17, v16
	v_add_f32_e32 v17, v3, v17
	v_max_f32_e32 v17, v198, v17
	s_cmp_eq_u32 s31, 3
	s_cbranch_scc1 .Ldil_norescale
	v_cmp_gt_f32_e32 vcc, v17, v198
	s_cbranch_vccz .Ldil_norescale
	v_sub_f32_e32 v16, v198, v17
	v_exp_f32_e32 v16, v16
	s_nop 0
	v_mul_f32_e32 v185, v185, v16
	v_pk_mul_f32 v[66:67], v[66:67], v[16:17] op_sel_hi:[1,0]
	v_pk_mul_f32 v[68:69], v[68:69], v[16:17] op_sel_hi:[1,0]
	v_pk_mul_f32 v[70:71], v[70:71], v[16:17] op_sel_hi:[1,0]
	v_pk_mul_f32 v[72:73], v[72:73], v[16:17] op_sel_hi:[1,0]
	v_pk_mul_f32 v[74:75], v[74:75], v[16:17] op_sel_hi:[1,0]
	v_pk_mul_f32 v[76:77], v[76:77], v[16:17] op_sel_hi:[1,0]
	v_pk_mul_f32 v[78:79], v[78:79], v[16:17] op_sel_hi:[1,0]
	v_pk_mul_f32 v[80:81], v[80:81], v[16:17] op_sel_hi:[1,0]
	v_pk_mul_f32 v[82:83], v[82:83], v[16:17] op_sel_hi:[1,0]
	v_pk_mul_f32 v[84:85], v[84:85], v[16:17] op_sel_hi:[1,0]
	v_pk_mul_f32 v[86:87], v[86:87], v[16:17] op_sel_hi:[1,0]
	v_pk_mul_f32 v[88:89], v[88:89], v[16:17] op_sel_hi:[1,0]
	v_pk_mul_f32 v[90:91], v[90:91], v[16:17] op_sel_hi:[1,0]
	v_pk_mul_f32 v[92:93], v[92:93], v[16:17] op_sel_hi:[1,0]
	v_pk_mul_f32 v[94:95], v[94:95], v[16:17] op_sel_hi:[1,0]
	v_pk_mul_f32 v[96:97], v[96:97], v[16:17] op_sel_hi:[1,0]
.Ldil_norescale:
	v_sub_f32_e32 v243, v17, v3
	v_mov_b32_e32 v198, v17
	v_sub_f32_e32 v98, v98, v243
	v_exp_f32_e32 v244, v98
	v_sub_f32_e32 v99, v99, v243
	v_exp_f32_e32 v99, v99
	v_sub_f32_e32 v100, v100, v243
	v_exp_f32_e32 v245, v100
	v_sub_f32_e32 v100, v101, v243
	v_exp_f32_e32 v101, v100
	v_sub_f32_e32 v100, v102, v243
	v_add_f32_e32 v98, 0, v244
	v_exp_f32_e32 v102, v100
	v_sub_f32_e32 v100, v103, v243
	v_add_f32_e32 v98, v99, v98
	v_exp_f32_e32 v103, v100
	v_sub_f32_e32 v100, v104, v243
	v_add_f32_e32 v98, v245, v98
	v_exp_f32_e32 v104, v100
	v_sub_f32_e32 v100, v105, v243
	v_add_f32_e32 v98, v101, v98
	v_exp_f32_e32 v105, v100
	v_sub_f32_e32 v100, v106, v243
	v_add_f32_e32 v98, v102, v98
	v_exp_f32_e32 v106, v100
	v_sub_f32_e32 v100, v107, v243
	v_add_f32_e32 v98, v103, v98
	v_exp_f32_e32 v107, v100
	v_sub_f32_e32 v100, v108, v243
	v_add_f32_e32 v98, v104, v98
	v_exp_f32_e32 v108, v100
	v_sub_f32_e32 v100, v109, v243
	v_add_f32_e32 v98, v105, v98
	v_exp_f32_e32 v109, v100
	v_sub_f32_e32 v100, v110, v243
	v_add_f32_e32 v98, v106, v98
	v_exp_f32_e32 v110, v100
	v_sub_f32_e32 v100, v111, v243
	v_add_f32_e32 v98, v107, v98
	v_exp_f32_e32 v111, v100
	v_sub_f32_e32 v100, v112, v243
	v_add_f32_e32 v98, v108, v98
	v_exp_f32_e32 v112, v100
	v_sub_f32_e32 v100, v113, v243
	v_add_f32_e32 v98, v109, v98
	v_exp_f32_e32 v113, v100
	v_add_f32_e32 v98, v110, v98
	v_add_f32_e32 v98, v111, v98
	v_add_f32_e32 v98, v112, v98
	v_add_f32_e32 v98, v113, v98
	v_mov_b32_e32 v100, v98
	s_nop 1
	v_permlane32_swap_b32_e32 v98, v100
	v_add_f32_e32 v98, v98, v100
	v_cvt_pk_bf16_f32 v100, v244, v99
	v_cvt_pk_bf16_f32 v101, v245, v101
	v_cvt_pk_bf16_f32 v102, v102, v103
	v_cvt_pk_bf16_f32 v103, v104, v105
	v_cvt_pk_bf16_f32 v104, v106, v107
	v_cvt_pk_bf16_f32 v105, v108, v109
	s_cbranch_scc1 .Ldil_pv0
	s_waitcnt lgkmcnt(6)
	v_mfma_f32_32x32x16_bf16 v[66:81], v[178:181], v[100:103], v[66:81]
	v_cvt_pk_bf16_f32 v106, v110, v111
	v_cvt_pk_bf16_f32 v107, v112, v113
	v_add_f32_e32 v185, v185, v98
	s_waitcnt lgkmcnt(2)
	v_mfma_f32_32x32x16_bf16 v[82:97], v[12:15], v[100:103], v[82:97]
	s_branch .Ldil_pv1
.Ldil_pv0:
	s_waitcnt lgkmcnt(6)
	v_mfma_f32_32x32x16_bf16 v[66:81], v[178:181], v[100:103], 0
	v_cvt_pk_bf16_f32 v106, v110, v111
	v_cvt_pk_bf16_f32 v107, v112, v113
	v_add_f32_e32 v185, v185, v98
	s_waitcnt lgkmcnt(2)
	v_mfma_f32_32x32x16_bf16 v[82:97], v[12:15], v[100:103], 0
.Ldil_pv1:
	v_mfma_f32_32x32x16_bf16 v[66:81], v[8:11], v[104:107], v[66:81]
	s_waitcnt lgkmcnt(0)
	v_mfma_f32_32x32x16_bf16 v[82:97], v[4:7], v[104:107], v[82:97]
	s_and_b64 vcc, exec, s[26:27]
	s_cbranch_vccz .Ldil_top
	v_mov_b32_e32 v98, v185
	v_mov_b32_e32 v17, v198
